# P0 transposes: third round (items 4096..4575) dealt to blocks 128..187 instead of 0..59
# baseline (speedup 1.0000x reference)
.LBB0_28:
	s_movk_i32 s98, 0
	s_cmpk_eq_u32 s92, 0x100
	s_cbranch_scc0 .Ltr3_pre
	s_cmpk_gt_u32 s96, 0x7f
	s_mov_b32 s98, 0x100000
	s_cselect_b32 s98, 0xfffffc00, s98

.LBB0_31:
	s_or_b64 exec, exec, s[16:17]
	v_cvt_f32_u32_e32 v7, v12
	v_sub_u32_e32 v17, 0, v12
	v_sub_u32_e32 v16, 0, v5
	v_max_i32_e32 v16, v5, v16
	v_rcp_iflag_f32_e32 v7, v7
	v_ashrrev_i32_e32 v13, 31, v5
	v_mul_f32_e32 v7, 0x4f7ffffe, v7
	v_cvt_u32_f32_e32 v7, v7
	v_mul_lo_u32 v17, v17, v7
	v_mul_hi_u32 v17, v7, v17
	v_add_u32_e32 v7, v7, v17
	v_mul_hi_u32 v7, v16, v7
	v_mul_lo_u32 v17, v7, v12
	v_sub_u32_e32 v16, v16, v17
	v_add_u32_e32 v40, 1, v7
	v_cmp_ge_u32_e64 s[0:1], v16, v12
	v_sub_u32_e32 v17, v16, v12
	s_nop 0
	v_cndmask_b32_e64 v7, v7, v40, s[0:1]
	v_cndmask_b32_e64 v16, v16, v17, s[0:1]
	v_add_u32_e32 v17, 1, v7
	v_cmp_ge_u32_e64 s[0:1], v16, v12
	s_nop 1
	v_cndmask_b32_e64 v7, v7, v17, s[0:1]
	v_xor_b32_e32 v7, v7, v13
	v_sub_u32_e32 v7, v7, v13
	v_mul_lo_u32 v12, v7, v12
	v_sub_u32_e32 v5, v5, v12
	v_lshlrev_b32_e32 v16, 6, v7
	v_lshlrev_b32_e32 v12, 6, v5
	v_or_b32_e32 v7, v16, v21
	v_ashrrev_i32_e32 v13, 31, v12
	v_ashrrev_i32_e32 v17, 31, v16
	v_or_b32_e32 v40, 4, v7
	v_or_b32_e32 v44, 8, v7
	v_lshl_add_u64 v[18:19], v[12:13], 2, v[18:19]
	v_mul_lo_u32 v13, v14, v17
	v_mul_lo_u32 v42, v15, v40
	v_mad_u64_u32 v[40:41], s[0:1], v14, v40, 0
	v_mul_lo_u32 v46, v15, v44
	v_mad_u64_u32 v[44:45], s[0:1], v14, v44, 0
	v_lshl_add_u64 v[18:19], v[18:19], 0, v[2:3]
	v_add3_u32 v41, v41, v13, v42
	v_add3_u32 v45, v45, v13, v46
	v_or_b32_e32 v46, 12, v7
	v_lshl_add_u64 v[40:41], v[40:41], 2, v[18:19]
	v_mul_lo_u32 v48, v15, v46
	v_mad_u64_u32 v[46:47], s[0:1], v14, v46, 0
	v_or_b32_e32 v52, 16, v7
	global_load_dwordx4 v[40:43], v[40:41], off
	v_add3_u32 v47, v47, v13, v48
	v_mul_lo_u32 v54, v15, v52
	v_mad_u64_u32 v[52:53], s[0:1], v14, v52, 0
	v_lshl_add_u64 v[44:45], v[44:45], 2, v[18:19]
	v_lshl_add_u64 v[48:49], v[46:47], 2, v[18:19]
	v_add3_u32 v53, v53, v13, v54
	v_or_b32_e32 v54, 20, v7
	global_load_dwordx4 v[44:47], v[44:45], off
	s_nop 0
	global_load_dwordx4 v[48:51], v[48:49], off
	v_mul_lo_u32 v56, v15, v54
	v_mad_u64_u32 v[54:55], s[0:1], v14, v54, 0
	v_add3_u32 v55, v55, v13, v56
	v_or_b32_e32 v60, 24, v7
	v_lshl_add_u64 v[52:53], v[52:53], 2, v[18:19]
	v_lshl_add_u64 v[56:57], v[54:55], 2, v[18:19]
	v_mul_lo_u32 v62, v15, v60
	v_mad_u64_u32 v[60:61], s[0:1], v14, v60, 0
	global_load_dwordx4 v[52:55], v[52:53], off
	s_nop 0
	global_load_dwordx4 v[56:59], v[56:57], off
	v_add3_u32 v61, v61, v13, v62
	v_or_b32_e32 v62, 28, v7
	v_mul_lo_u32 v64, v15, v62
	v_mad_u64_u32 v[62:63], s[0:1], v14, v62, 0
	v_add3_u32 v63, v63, v13, v64
	v_lshl_add_u64 v[60:61], v[60:61], 2, v[18:19]
	v_lshl_add_u64 v[64:65], v[62:63], 2, v[18:19]
	v_or_b32_e32 v72, 32, v7
	global_load_dwordx4 v[60:63], v[60:61], off
	s_nop 0
	global_load_dwordx4 v[64:67], v[64:65], off
	v_mul_lo_u32 v70, v15, v7
	v_mad_u64_u32 v[68:69], s[0:1], v14, v7, 0
	v_or_b32_e32 v74, 36, v7
	v_mul_lo_u32 v75, v15, v72
	v_mad_u64_u32 v[72:73], s[0:1], v14, v72, 0
	v_add3_u32 v69, v69, v13, v70
	v_mul_lo_u32 v76, v15, v74
	v_add3_u32 v73, v73, v13, v75
	v_mad_u64_u32 v[74:75], s[0:1], v14, v74, 0
	v_lshl_add_u64 v[68:69], v[68:69], 2, v[18:19]
	v_add3_u32 v75, v75, v13, v76
	v_or_b32_e32 v80, 40, v7
	global_load_dwordx4 v[68:71], v[68:69], off
	v_lshl_add_u64 v[72:73], v[72:73], 2, v[18:19]
	v_lshl_add_u64 v[76:77], v[74:75], 2, v[18:19]
	v_mul_lo_u32 v82, v15, v80
	v_mad_u64_u32 v[80:81], s[0:1], v14, v80, 0
	global_load_dwordx4 v[72:75], v[72:73], off
	s_nop 0
	global_load_dwordx4 v[76:79], v[76:77], off
	v_add3_u32 v81, v81, v13, v82
	v_or_b32_e32 v82, 44, v7
	v_mul_lo_u32 v84, v15, v82
	v_mad_u64_u32 v[82:83], s[0:1], v14, v82, 0
	v_add3_u32 v83, v83, v13, v84
	v_lshl_add_u64 v[80:81], v[80:81], 2, v[18:19]
	v_lshl_add_u64 v[84:85], v[82:83], 2, v[18:19]
	v_or_b32_e32 v88, 48, v7
	global_load_dwordx4 v[80:83], v[80:81], off
	s_nop 0
	global_load_dwordx4 v[84:87], v[84:85], off
	v_mul_lo_u32 v90, v15, v88
	v_mad_u64_u32 v[88:89], s[0:1], v14, v88, 0
	v_add3_u32 v89, v89, v13, v90
	v_or_b32_e32 v92, 52, v7
	v_lshl_add_u64 v[88:89], v[88:89], 2, v[18:19]
	v_mul_lo_u32 v94, v15, v92
	v_mad_u64_u32 v[92:93], s[0:1], v14, v92, 0
	global_load_dwordx4 v[88:91], v[88:89], off
	v_add3_u32 v93, v93, v13, v94
	v_or_b32_e32 v94, 56, v7
	v_lshl_add_u64 v[92:93], v[92:93], 2, v[18:19]
	v_mul_lo_u32 v95, v15, v94
	v_mad_u64_u32 v[96:97], s[0:1], v14, v94, 0
	v_add3_u32 v97, v97, v13, v95
	v_or_b32_e32 v7, 60, v7
	global_load_dwordx4 v[92:95], v[92:93], off
	v_mul_lo_u32 v100, v15, v7
	v_lshl_add_u64 v[96:97], v[96:97], 2, v[18:19]
	v_mad_u64_u32 v[14:15], s[0:1], v14, v7, 0
	global_load_dwordx4 v[96:99], v[96:97], off
	v_add3_u32 v15, v15, v13, v100
	v_lshl_add_u64 v[14:15], v[14:15], 2, v[18:19]
	global_load_dwordx4 v[100:103], v[14:15], off
	v_add_u32_e32 v7, 0x410, v39
	s_waitcnt vmcnt(15)
	ds_write2_b32 v7, v40, v41 offset1:1
	v_add_u32_e32 v7, 0x418, v39
	ds_write2_b32 v7, v42, v43 offset1:1
	v_add_u32_e32 v7, 0x820, v39
	v_cmp_eq_u32_e64 s[0:1], 64, v5
	v_add_u32_e32 v5, 0x828, v39
	s_waitcnt vmcnt(14)
	ds_write2_b32 v7, v44, v45 offset1:1
	v_add_u32_e32 v7, 0xc30, v39
	ds_write2_b32 v5, v46, v47 offset1:1
	s_waitcnt vmcnt(13)
	ds_write2_b32 v7, v48, v49 offset1:1
	v_add_u32_e32 v5, 0xc38, v39
	ds_write2_b32 v5, v50, v51 offset1:1
	v_add_u32_e32 v5, 0x1040, v39
	s_waitcnt vmcnt(12)
	ds_write2_b32 v5, v52, v53 offset1:1
	v_add_u32_e32 v5, 0x1048, v39
	ds_write2_b32 v5, v54, v55 offset1:1
	v_add_u32_e32 v5, 0x1450, v39
	s_waitcnt vmcnt(11)
	ds_write2_b32 v5, v56, v57 offset1:1
	v_add_u32_e32 v5, 0x1458, v39
	ds_write2_b32 v5, v58, v59 offset1:1
	v_add_u32_e32 v5, 0x1860, v39
	s_waitcnt vmcnt(10)
	ds_write2_b32 v5, v60, v61 offset1:1
	v_add_u32_e32 v5, 0x1868, v39
	ds_write2_b32 v5, v62, v63 offset1:1
	v_add_u32_e32 v5, 0x1c70, v39
	s_waitcnt vmcnt(9)
	ds_write2_b32 v5, v64, v65 offset1:1
	v_add_u32_e32 v5, 0x1c78, v39
	ds_write2_b32 v5, v66, v67 offset1:1
	v_add_u32_e32 v5, 0x2080, v39
	s_waitcnt vmcnt(8)
	ds_write2_b32 v39, v68, v69 offset1:1
	ds_write2_b32 v39, v70, v71 offset0:2 offset1:3
	s_and_b64 s[0:1], vcc, s[0:1]
	s_or_b64 vcc, s[12:13], s[0:1]
	v_cndmask_b32_e32 v7, v22, v24, vcc
	v_lshl_add_u32 v7, v7, 2, v23
	s_waitcnt vmcnt(7)
	ds_write2_b32 v5, v72, v73 offset1:1
	v_add_u32_e32 v5, 0x2088, v39
	ds_write2_b32 v5, v74, v75 offset1:1
	v_add_u32_e32 v5, 0x2490, v39
	s_waitcnt vmcnt(6)
	ds_write2_b32 v5, v76, v77 offset1:1
	v_add_u32_e32 v5, 0x2498, v39
	ds_write2_b32 v5, v78, v79 offset1:1
	v_add_u32_e32 v5, 0x28a0, v39
	v_lshl_add_u64 v[8:9], v[16:17], 1, v[8:9]
	s_waitcnt vmcnt(5)
	ds_write2_b32 v5, v80, v81 offset1:1
	v_add_u32_e32 v5, 0x28a8, v39
	ds_write2_b32 v5, v82, v83 offset1:1
	v_add_u32_e32 v5, 0x2cb0, v39
	s_waitcnt vmcnt(4)
	ds_write2_b32 v5, v84, v85 offset1:1
	v_add_u32_e32 v5, 0x2cb8, v39
	ds_write2_b32 v5, v86, v87 offset1:1
	v_add_u32_e32 v5, 0x30c0, v39
	s_waitcnt vmcnt(3)
	ds_write2_b32 v5, v88, v89 offset1:1
	v_add_u32_e32 v5, 0x30c8, v39
	ds_write2_b32 v5, v90, v91 offset1:1
	v_add_u32_e32 v5, 0x34d0, v39
	s_waitcnt vmcnt(2)
	ds_write2_b32 v5, v92, v93 offset1:1
	v_add_u32_e32 v5, 0x34d8, v39
	ds_write2_b32 v5, v94, v95 offset1:1
	v_add_u32_e32 v5, 0x38e0, v39
	s_waitcnt vmcnt(1)
	ds_write2_b32 v5, v96, v97 offset1:1
	v_add_u32_e32 v5, 0x38e8, v39
	ds_write2_b32 v5, v98, v99 offset1:1
	v_add_u32_e32 v5, 0x3cf0, v39
	s_waitcnt vmcnt(0)
	ds_write2_b32 v5, v100, v101 offset1:1
	v_add_u32_e32 v5, 0x3cf8, v39
	ds_write2_b32 v5, v102, v103 offset1:1
	s_waitcnt lgkmcnt(0)
	ds_read2_b32 v[14:15], v7 offset1:65
	ds_read2_b32 v[16:17], v7 offset0:130 offset1:195
	v_add_u32_e32 v7, 0x400, v7
	ds_read2_b32 v[18:19], v7 offset0:4 offset1:69
	ds_read2_b32 v[40:41], v7 offset0:134 offset1:199
	v_mov_b32_e32 v5, v3
	v_lshl_add_u64 v[8:9], v[8:9], 0, v[4:5]
	v_or_b32_e32 v5, v12, v22
	s_waitcnt lgkmcnt(3)
	v_cvt_pk_bf16_f32 v14, v14, v15
	s_waitcnt lgkmcnt(2)
	v_cvt_pk_bf16_f32 v15, v16, v17
	s_waitcnt lgkmcnt(1)
	v_cvt_pk_bf16_f32 v16, v18, v19
	v_mad_i64_i32 v[18:19], s[0:1], v6, v5, 0
	v_cndmask_b32_e32 v5, v25, v26, vcc
	v_lshl_add_u32 v5, v5, 2, v23
	s_waitcnt lgkmcnt(0)
	v_cvt_pk_bf16_f32 v17, v40, v41
	ds_read2_b32 v[40:41], v5 offset1:65
	ds_read2_b32 v[42:43], v5 offset0:130 offset1:195
	v_add_u32_e32 v5, 0x400, v5
	ds_read2_b32 v[44:45], v5 offset0:4 offset1:69
	ds_read2_b32 v[46:47], v5 offset0:134 offset1:199
	v_lshl_add_u64 v[18:19], v[18:19], 1, v[8:9]
	v_or_b32_e32 v5, v12, v25
	global_store_dwordx4 v[18:19], v[14:17], off
	v_mad_i64_i32 v[18:19], s[0:1], v6, v5, 0
	v_cndmask_b32_e32 v5, v27, v28, vcc
	v_lshl_add_u32 v5, v5, 2, v23
	s_waitcnt lgkmcnt(3)
	v_cvt_pk_bf16_f32 v14, v40, v41
	s_waitcnt lgkmcnt(2)
	v_cvt_pk_bf16_f32 v15, v42, v43
	ds_read2_b32 v[40:41], v5 offset1:65
	ds_read2_b32 v[42:43], v5 offset0:130 offset1:195
	v_add_u32_e32 v5, 0x400, v5
	s_waitcnt lgkmcnt(3)
	v_cvt_pk_bf16_f32 v16, v44, v45
	s_waitcnt lgkmcnt(2)
	v_cvt_pk_bf16_f32 v17, v46, v47
	ds_read2_b32 v[44:45], v5 offset0:4 offset1:69
	ds_read2_b32 v[46:47], v5 offset0:134 offset1:199
	v_lshl_add_u64 v[18:19], v[18:19], 1, v[8:9]
	v_or_b32_e32 v5, v12, v27
	global_store_dwordx4 v[18:19], v[14:17], off
	v_mad_i64_i32 v[18:19], s[0:1], v6, v5, 0
	v_cndmask_b32_e32 v5, v29, v30, vcc
	v_lshl_add_u32 v5, v5, 2, v23
	s_waitcnt lgkmcnt(3)
	v_cvt_pk_bf16_f32 v14, v40, v41
	s_waitcnt lgkmcnt(2)
	v_cvt_pk_bf16_f32 v15, v42, v43
	ds_read2_b32 v[40:41], v5 offset1:65
	ds_read2_b32 v[42:43], v5 offset0:130 offset1:195
	v_add_u32_e32 v5, 0x400, v5
	s_waitcnt lgkmcnt(3)
	v_cvt_pk_bf16_f32 v16, v44, v45
	s_waitcnt lgkmcnt(2)
	v_cvt_pk_bf16_f32 v17, v46, v47
	ds_read2_b32 v[44:45], v5 offset0:4 offset1:69
	ds_read2_b32 v[46:47], v5 offset0:134 offset1:199
	v_lshl_add_u64 v[18:19], v[18:19], 1, v[8:9]
	v_or_b32_e32 v5, v12, v29
	global_store_dwordx4 v[18:19], v[14:17], off
	v_mad_i64_i32 v[18:19], s[0:1], v6, v5, 0
	v_cndmask_b32_e32 v5, v31, v32, vcc
	v_lshl_add_u32 v5, v5, 2, v23
	s_waitcnt lgkmcnt(3)
	v_cvt_pk_bf16_f32 v14, v40, v41
	s_waitcnt lgkmcnt(2)
	v_cvt_pk_bf16_f32 v15, v42, v43
	ds_read2_b32 v[40:41], v5 offset1:65
	ds_read2_b32 v[42:43], v5 offset0:130 offset1:195
	v_add_u32_e32 v5, 0x400, v5
	s_waitcnt lgkmcnt(3)
	v_cvt_pk_bf16_f32 v16, v44, v45
	s_waitcnt lgkmcnt(2)
	v_cvt_pk_bf16_f32 v17, v46, v47
	ds_read2_b32 v[44:45], v5 offset0:4 offset1:69
	ds_read2_b32 v[46:47], v5 offset0:134 offset1:199
	v_lshl_add_u64 v[18:19], v[18:19], 1, v[8:9]
	v_or_b32_e32 v5, v12, v31
	global_store_dwordx4 v[18:19], v[14:17], off
	v_mad_i64_i32 v[18:19], s[0:1], v6, v5, 0
	v_cndmask_b32_e32 v5, v33, v34, vcc
	v_lshl_add_u32 v5, v5, 2, v23
	s_waitcnt lgkmcnt(3)
	v_cvt_pk_bf16_f32 v14, v40, v41
	s_waitcnt lgkmcnt(2)
	v_cvt_pk_bf16_f32 v15, v42, v43
	ds_read2_b32 v[40:41], v5 offset1:65
	ds_read2_b32 v[42:43], v5 offset0:130 offset1:195
	v_add_u32_e32 v5, 0x400, v5
	s_waitcnt lgkmcnt(3)
	v_cvt_pk_bf16_f32 v16, v44, v45
	s_waitcnt lgkmcnt(2)
	v_cvt_pk_bf16_f32 v17, v46, v47
	ds_read2_b32 v[44:45], v5 offset0:4 offset1:69
	ds_read2_b32 v[46:47], v5 offset0:134 offset1:199
	v_lshl_add_u64 v[18:19], v[18:19], 1, v[8:9]
	v_or_b32_e32 v5, v12, v33
	global_store_dwordx4 v[18:19], v[14:17], off
	v_mad_i64_i32 v[18:19], s[0:1], v6, v5, 0
	v_cndmask_b32_e32 v5, v35, v36, vcc
	v_lshl_add_u32 v5, v5, 2, v23
	s_waitcnt lgkmcnt(3)
	v_cvt_pk_bf16_f32 v14, v40, v41
	s_waitcnt lgkmcnt(2)
	v_cvt_pk_bf16_f32 v15, v42, v43
	ds_read2_b32 v[40:41], v5 offset1:65
	ds_read2_b32 v[42:43], v5 offset0:130 offset1:195
	v_add_u32_e32 v5, 0x400, v5
	s_waitcnt lgkmcnt(3)
	v_cvt_pk_bf16_f32 v16, v44, v45
	s_waitcnt lgkmcnt(2)
	v_cvt_pk_bf16_f32 v17, v46, v47
	ds_read2_b32 v[44:45], v5 offset0:4 offset1:69
	ds_read2_b32 v[46:47], v5 offset0:134 offset1:199
	v_lshl_add_u64 v[18:19], v[18:19], 1, v[8:9]
	v_or_b32_e32 v5, v12, v35
	global_store_dwordx4 v[18:19], v[14:17], off
	v_mad_i64_i32 v[18:19], s[0:1], v6, v5, 0
	v_cndmask_b32_e32 v5, v37, v38, vcc
	v_lshl_add_u32 v5, v5, 2, v23
	s_waitcnt lgkmcnt(3)
	v_cvt_pk_bf16_f32 v14, v40, v41
	s_waitcnt lgkmcnt(2)
	v_cvt_pk_bf16_f32 v15, v42, v43
	ds_read2_b32 v[40:41], v5 offset1:65
	ds_read2_b32 v[42:43], v5 offset0:130 offset1:195
	v_add_u32_e32 v5, 0x400, v5
	s_waitcnt lgkmcnt(3)
	v_cvt_pk_bf16_f32 v16, v44, v45
	s_waitcnt lgkmcnt(2)
	v_cvt_pk_bf16_f32 v17, v46, v47
	ds_read2_b32 v[44:45], v5 offset0:4 offset1:69
	ds_read2_b32 v[46:47], v5 offset0:134 offset1:199
	v_or_b32_e32 v5, v12, v37
	v_lshl_add_u64 v[18:19], v[18:19], 1, v[8:9]
	v_mad_i64_i32 v[6:7], s[0:1], v6, v5, 0
	global_store_dwordx4 v[18:19], v[14:17], off
	v_lshl_add_u64 v[6:7], v[6:7], 1, v[8:9]
	v_readlane_b32 s0, v254, 40
	s_waitcnt lgkmcnt(3)
	v_cvt_pk_bf16_f32 v14, v40, v41
	s_waitcnt lgkmcnt(2)
	v_cvt_pk_bf16_f32 v15, v42, v43
	s_waitcnt lgkmcnt(1)
	v_cvt_pk_bf16_f32 v16, v44, v45
	s_waitcnt lgkmcnt(0)
	v_cvt_pk_bf16_f32 v17, v46, v47
	global_store_dwordx4 v[6:7], v[14:17], off
	v_add_u32_e32 v20, s0, v20
	v_cmp_lt_u32_e32 vcc, 0xfff, v20
	v_add_u32_e32 v5, s98, v20
	v_cndmask_b32_e32 v20, v20, v5, vcc
	s_movk_i32 s0, 0x11df
	s_waitcnt lgkmcnt(0)
	v_cmp_lt_i32_e32 vcc, s0, v20
	s_or_b64 s[6:7], vcc, s[6:7]
	v_readlane_b32 s1, v254, 41
	s_andn2_b64 exec, exec, s[6:7]
	s_cbranch_execz .LBB0_49
